# norm phases: the sample row of the third loop iteration (128 waves) is fetched during the second iteration and copied in, instead of an exposed load round trip on the phase's critical path
# speedup vs baseline: 1.0099x; 1.0018x over previous
.LBB0_632:
	v_lshl_add_u64 v[4:5], v[80:81], 0, v[78:79]
	v_cmp_lt_i32_e32 vcc, 0x3fff, v0
	s_cbranch_vccnz .Ln3a_third
		global_load_dwordx4 v[64:67], v[4:5], off
		global_load_dwordx4 v[60:63], v[4:5], off offset:1024
		global_load_dwordx4 v[56:59], v[4:5], off offset:2048
		global_load_dwordx4 v[52:55], v[4:5], off offset:3072
	v_add_u32_e32 v216, 0xffffe000, v0
	v_cmp_gt_u32_e32 vcc, 128, v216
	s_cbranch_vccz .Ln3a_join
	v_readlane_b32 s16, v252, 19
	v_readlane_b32 s17, v252, 20
	s_nop 3
	v_lshl_add_u64 v[216:217], v[4:5], 0, s[16:17]
	global_load_dwordx4 v[220:223], v[216:217], off
	global_load_dwordx4 v[224:227], v[216:217], off offset:1024
	global_load_dwordx4 v[228:231], v[216:217], off offset:2048
	global_load_dwordx4 v[232:235], v[216:217], off offset:3072
	s_branch .Ln3a_join
.Ln3a_third:
	v_mov_b64_e32 v[64:65], v[220:221]
	v_mov_b64_e32 v[66:67], v[222:223]
	v_mov_b64_e32 v[60:61], v[224:225]
	v_mov_b64_e32 v[62:63], v[226:227]
	v_mov_b64_e32 v[56:57], v[228:229]
	v_mov_b64_e32 v[58:59], v[230:231]
	v_mov_b64_e32 v[52:53], v[232:233]
	v_mov_b64_e32 v[54:55], v[234:235]
.Ln3a_join:
	v_add_u32_e32 v110, s68, v0
	s_movk_i32 s0, 0x4080
	v_cmp_gt_i32_e64 s[40:41], s0, v110
	v_mov_b32_e32 v16, 0
	v_mov_b32_e32 v36, 0
	v_mov_b32_e32 v37, 0
	v_mov_b32_e32 v38, 0
	v_mov_b32_e32 v39, 0
	v_mov_b32_e32 v40, 0
	v_mov_b32_e32 v41, 0
	v_mov_b32_e32 v42, 0
	v_mov_b32_e32 v43, 0
	v_mov_b32_e32 v44, 0
	v_mov_b32_e32 v45, 0
	v_mov_b32_e32 v46, 0
	v_mov_b32_e32 v47, 0
	v_mov_b32_e32 v48, 0
	v_mov_b32_e32 v49, 0
	v_mov_b32_e32 v50, 0
	v_mov_b32_e32 v51, 0
	s_and_saveexec_b64 s[0:1], s[40:41]
	s_cbranch_execz .LBB0_634
	v_lshl_add_u64 v[4:5], v[82:83], 0, v[78:79]
	global_load_dwordx4 v[48:51], v[4:5], off
	global_load_dwordx4 v[44:47], v[4:5], off offset:1024
	global_load_dwordx4 v[40:43], v[4:5], off offset:2048
	global_load_dwordx4 v[36:39], v[4:5], off offset:3072

.LBB0_716:
	v_lshlrev_b64 v[4:5], 12, v[4:5]
	v_lshl_add_u64 v[4:5], v[6:7], 0, v[4:5]
	v_lshlrev_b32_e32 v82, 2, v68
	v_mov_b32_e32 v83, v2
	v_lshl_add_u64 v[4:5], v[4:5], 0, v[82:83]
	v_cmp_le_i32_e32 vcc, 0, v72
	s_cbranch_vccnz .Ln3b_third
		flat_load_dwordx4 v[64:67], v[4:5]
		flat_load_dwordx4 v[60:63], v[4:5] offset:1024
		flat_load_dwordx4 v[56:59], v[4:5] offset:2048
		flat_load_dwordx4 v[52:55], v[4:5] offset:3072
	v_add_u32_e32 v216, 0x2000, v72
	v_cmp_gt_u32_e32 vcc, 128, v216
	s_cbranch_vccz .Ln3b_join
	s_and_b64 vcc, exec, s[6:7]
	s_cbranch_vccz .Ln3b_first
	v_add_u32_e32 v216, 0x2000, v77
	v_mov_b64_e32 v[218:219], s[60:61]
	s_branch .Ln3b_addr
.Ln3b_first:
	v_mov_b64_e32 v[218:219], s[2:3]
.Ln3b_addr:
	v_mov_b32_e32 v217, 0
	v_lshlrev_b64 v[216:217], 12, v[216:217]
	v_lshl_add_u64 v[216:217], v[218:219], 0, v[216:217]
	v_lshl_add_u64 v[216:217], v[216:217], 0, v[82:83]
	global_load_dwordx4 v[220:223], v[216:217], off
	global_load_dwordx4 v[224:227], v[216:217], off offset:1024
	global_load_dwordx4 v[228:231], v[216:217], off offset:2048
	global_load_dwordx4 v[232:235], v[216:217], off offset:3072
	s_branch .Ln3b_join

.Ln3b_join:
	v_add_u32_e32 v94, s68, v72
	v_add_u32_e32 v92, 0x4000, v94
	s_movk_i32 s10, 0x4080
	v_cndmask_b32_e64 v4, 0, 1, s[6:7]
	v_cmp_gt_i32_e64 s[42:43], s10, v92
	v_mov_b32_e32 v51, 0
	v_cmp_ne_u32_e64 s[44:45], 1, v4
	v_mov_b32_e32 v50, 0
	v_mov_b32_e32 v49, 0
	v_mov_b32_e32 v48, 0
	v_mov_b32_e32 v47, 0
	v_mov_b32_e32 v46, 0
	v_mov_b32_e32 v45, 0
	v_mov_b32_e32 v44, 0
	v_mov_b32_e32 v43, 0
	v_mov_b32_e32 v42, 0
	v_mov_b32_e32 v41, 0
	v_mov_b32_e32 v40, 0
	v_mov_b32_e32 v35, 0
	v_mov_b32_e32 v34, 0
	v_mov_b32_e32 v33, 0
	v_mov_b32_e32 v32, 0
	s_and_saveexec_b64 s[10:11], s[42:43]
	s_cbranch_execz .LBB0_726
	s_and_b64 vcc, exec, s[44:45]
	s_mov_b64 s[12:13], -1
	s_cbranch_vccnz .LBB0_719
	v_ashrrev_i32_e32 v93, 31, v92
	s_mov_b64 s[12:13], 0
	v_mov_b64_e32 v[4:5], v[92:93]
